# v27: v25 + 4/4 LDS-DMA balance in the other four GEMM K-loops (A0 half-tile staging moved to the following SP1 segment)
# speedup vs baseline: 1.0078x; 1.0078x over previous
.LBB0_230:
	s_add_u32 s98, s0, 0xfff00000
	s_addc_u32 s99, s1, -1
	s_add_u32 s28, s0, 0xfff00080
	s_addc_u32 s29, s1, -1
	s_add_i32 s51, 0, 0x10000
	s_cmp_eq_u32 s50, 60
	s_cselect_b32 s31, s34, s29
	s_cselect_b32 s30, s35, s28
	v_add_u32_e32 v0, s51, v179
	s_cselect_b32 s29, s27, s43
	s_cselect_b32 s28, s40, s41
	s_add_i32 s77, 0, 0x14000
	ds_read_b128 v[130:133], v0
	ds_read_b128 v[134:137], v0 offset:1024
	ds_read_b128 v[138:141], v0 offset:2048
	ds_read_b128 v[142:145], v0 offset:3072
	v_add_u32_e32 v0, s77, v179
	ds_read_b128 v[146:149], v0
	ds_read_b128 v[150:153], v0 offset:1024
	ds_read_b128 v[154:157], v0 offset:2048
	ds_read_b128 v[158:161], v0 offset:3072
	s_mov_b32 m0, s54
	ds_read_b128 v[174:177], v192
	ds_read_b128 v[180:183], v192 offset:1024
	ds_read_b128 v[184:187], v192 offset:2048
	ds_read_b128 v[188:191], v192 offset:3072
	ds_read_b128 v[200:203], v192 offset:4096
	ds_read_b128 v[204:207], v192 offset:5120
	ds_read_b128 v[208:211], v192 offset:6144
	ds_read_b128 v[212:215], v192 offset:7168
	global_load_lds_dwordx4 v168, s[98:99]
	s_mov_b32 m0, s55
	s_nop 0
	global_load_lds_dwordx4 v164, s[98:99]
	s_add_i32 m0, s14, 0xc000
	s_nop 0
	global_load_lds_dwordx4 v170, s[0:1]
	s_add_i32 m0, s14, 0xe000
	s_nop 0
	global_load_lds_dwordx4 v172, s[0:1]
	s_waitcnt vmcnt(8)
	s_waitcnt lgkmcnt(0)
	s_barrier
	s_waitcnt lgkmcnt(0)
	v_mfma_f32_16x16x32_bf16 v[126:129], v[130:133], v[174:177], v[126:129]
	v_mfma_f32_16x16x32_bf16 v[126:129], v[134:137], v[180:183], v[126:129]
	v_mfma_f32_16x16x32_bf16 v[110:113], v[130:133], v[184:187], v[110:113]
	v_mfma_f32_16x16x32_bf16 v[110:113], v[134:137], v[188:191], v[110:113]
	v_mfma_f32_16x16x32_bf16 v[94:97], v[130:133], v[200:203], v[94:97]
	v_mfma_f32_16x16x32_bf16 v[94:97], v[134:137], v[204:207], v[94:97]
	v_mfma_f32_16x16x32_bf16 v[78:81], v[130:133], v[208:211], v[78:81]
	v_mfma_f32_16x16x32_bf16 v[78:81], v[134:137], v[212:215], v[78:81]
	v_mfma_f32_16x16x32_bf16 v[122:125], v[138:141], v[174:177], v[122:125]
	v_mfma_f32_16x16x32_bf16 v[122:125], v[142:145], v[180:183], v[122:125]
	v_mfma_f32_16x16x32_bf16 v[106:109], v[138:141], v[184:187], v[106:109]
	v_mfma_f32_16x16x32_bf16 v[106:109], v[142:145], v[188:191], v[106:109]
	v_mfma_f32_16x16x32_bf16 v[90:93], v[138:141], v[200:203], v[90:93]
	v_mfma_f32_16x16x32_bf16 v[90:93], v[142:145], v[204:207], v[90:93]
	v_mfma_f32_16x16x32_bf16 v[74:77], v[138:141], v[208:211], v[74:77]
	v_mfma_f32_16x16x32_bf16 v[74:77], v[142:145], v[212:215], v[74:77]
	v_mfma_f32_16x16x32_bf16 v[118:121], v[146:149], v[174:177], v[118:121]
	v_mfma_f32_16x16x32_bf16 v[118:121], v[150:153], v[180:183], v[118:121]
	v_mfma_f32_16x16x32_bf16 v[102:105], v[146:149], v[184:187], v[102:105]
	v_mfma_f32_16x16x32_bf16 v[102:105], v[150:153], v[188:191], v[102:105]
	v_mfma_f32_16x16x32_bf16 v[86:89], v[146:149], v[200:203], v[86:89]
	v_mfma_f32_16x16x32_bf16 v[86:89], v[150:153], v[204:207], v[86:89]
	v_mfma_f32_16x16x32_bf16 v[70:73], v[146:149], v[208:211], v[70:73]
	v_mfma_f32_16x16x32_bf16 v[70:73], v[150:153], v[212:215], v[70:73]
	v_mfma_f32_16x16x32_bf16 v[114:117], v[154:157], v[174:177], v[114:117]
	v_mfma_f32_16x16x32_bf16 v[114:117], v[158:161], v[180:183], v[114:117]
	v_mfma_f32_16x16x32_bf16 v[98:101], v[154:157], v[184:187], v[98:101]
	v_mfma_f32_16x16x32_bf16 v[98:101], v[158:161], v[188:191], v[98:101]
	v_mfma_f32_16x16x32_bf16 v[82:85], v[154:157], v[200:203], v[82:85]
	v_mfma_f32_16x16x32_bf16 v[82:85], v[158:161], v[204:207], v[82:85]
	v_mfma_f32_16x16x32_bf16 v[66:69], v[154:157], v[208:211], v[66:69]
	v_mfma_f32_16x16x32_bf16 v[66:69], v[158:161], v[212:215], v[66:69]
	s_barrier
	s_add_i32 s51, s51, s9
	s_mov_b32 m0, s51
	ds_read_b128 v[174:177], v192 offset:16384
	ds_read_b128 v[180:183], v192 offset:17408
	ds_read_b128 v[184:187], v192 offset:18432
	ds_read_b128 v[188:191], v192 offset:19456
	ds_read_b128 v[200:203], v192 offset:20480
	ds_read_b128 v[204:207], v192 offset:21504
	ds_read_b128 v[208:211], v192 offset:22528
	ds_read_b128 v[212:215], v192 offset:23552
	global_load_lds_dwordx4 v166, s[28:29]
	s_add_i32 m0, s51, 0x2000
	s_add_u32 s80, s28, 0x100000
	s_addc_u32 s81, s29, 0
	s_add_i32 s51, s77, s9
	global_load_lds_dwordx4 v162, s[28:29]
	s_mov_b32 m0, s51
	s_nop 0
	global_load_lds_dwordx4 v166, s[80:81]
	s_add_i32 m0, s51, 0x2000
	s_nop 0
	global_load_lds_dwordx4 v162, s[80:81]
	s_waitcnt vmcnt(6)
	s_waitcnt lgkmcnt(0)
	s_barrier
	s_waitcnt lgkmcnt(0)
	v_mfma_f32_16x16x32_bf16 v[62:65], v[130:133], v[174:177], v[62:65]
	v_mfma_f32_16x16x32_bf16 v[62:65], v[134:137], v[180:183], v[62:65]
	v_mfma_f32_16x16x32_bf16 v[46:49], v[130:133], v[184:187], v[46:49]
	v_mfma_f32_16x16x32_bf16 v[46:49], v[134:137], v[188:191], v[46:49]
	v_mfma_f32_16x16x32_bf16 v[30:33], v[130:133], v[200:203], v[30:33]
	v_mfma_f32_16x16x32_bf16 v[30:33], v[134:137], v[204:207], v[30:33]
	v_mfma_f32_16x16x32_bf16 v[14:17], v[130:133], v[208:211], v[14:17]
	v_mfma_f32_16x16x32_bf16 v[14:17], v[134:137], v[212:215], v[14:17]
	v_mfma_f32_16x16x32_bf16 v[58:61], v[138:141], v[174:177], v[58:61]
	v_mfma_f32_16x16x32_bf16 v[58:61], v[142:145], v[180:183], v[58:61]
	v_mfma_f32_16x16x32_bf16 v[42:45], v[138:141], v[184:187], v[42:45]
	v_mfma_f32_16x16x32_bf16 v[42:45], v[142:145], v[188:191], v[42:45]
	v_mfma_f32_16x16x32_bf16 v[26:29], v[138:141], v[200:203], v[26:29]
	v_mfma_f32_16x16x32_bf16 v[26:29], v[142:145], v[204:207], v[26:29]
	v_mfma_f32_16x16x32_bf16 v[10:13], v[138:141], v[208:211], v[10:13]
	v_mfma_f32_16x16x32_bf16 v[10:13], v[142:145], v[212:215], v[10:13]
	v_mfma_f32_16x16x32_bf16 v[54:57], v[146:149], v[174:177], v[54:57]
	v_mfma_f32_16x16x32_bf16 v[54:57], v[150:153], v[180:183], v[54:57]
	v_mfma_f32_16x16x32_bf16 v[38:41], v[146:149], v[184:187], v[38:41]
	v_mfma_f32_16x16x32_bf16 v[38:41], v[150:153], v[188:191], v[38:41]
	v_mfma_f32_16x16x32_bf16 v[22:25], v[146:149], v[200:203], v[22:25]
	v_mfma_f32_16x16x32_bf16 v[22:25], v[150:153], v[204:207], v[22:25]
	v_mfma_f32_16x16x32_bf16 v[6:9], v[146:149], v[208:211], v[6:9]
	v_mfma_f32_16x16x32_bf16 v[6:9], v[150:153], v[212:215], v[6:9]
	v_mfma_f32_16x16x32_bf16 v[50:53], v[154:157], v[174:177], v[50:53]
	v_mfma_f32_16x16x32_bf16 v[50:53], v[158:161], v[180:183], v[50:53]
	v_mfma_f32_16x16x32_bf16 v[34:37], v[154:157], v[184:187], v[34:37]
	v_mfma_f32_16x16x32_bf16 v[34:37], v[158:161], v[188:191], v[34:37]
	v_mfma_f32_16x16x32_bf16 v[18:21], v[154:157], v[200:203], v[18:21]
	v_mfma_f32_16x16x32_bf16 v[18:21], v[158:161], v[204:207], v[18:21]
	v_mfma_f32_16x16x32_bf16 v[2:5], v[154:157], v[208:211], v[2:5]
	v_mfma_f32_16x16x32_bf16 v[2:5], v[158:161], v[212:215], v[2:5]
	s_barrier
	s_add_i32 s51, 0, 0x18000
	v_add_u32_e32 v0, s51, v179
	s_add_i32 s77, 0, 0x1c000
	ds_read_b128 v[130:133], v0
	ds_read_b128 v[134:137], v0 offset:1024
	ds_read_b128 v[138:141], v0 offset:2048
	ds_read_b128 v[142:145], v0 offset:3072
	v_add_u32_e32 v0, s77, v179
	ds_read_b128 v[146:149], v0
	ds_read_b128 v[150:153], v0 offset:1024
	ds_read_b128 v[154:157], v0 offset:2048
	ds_read_b128 v[158:161], v0 offset:3072
	s_mov_b32 m0, s14
	ds_read_b128 v[174:177], v192 offset:32768
	ds_read_b128 v[180:183], v192 offset:33792
	ds_read_b128 v[184:187], v192 offset:34816
	ds_read_b128 v[188:191], v192 offset:35840
	ds_read_b128 v[200:203], v192 offset:36864
	ds_read_b128 v[204:207], v192 offset:37888
	ds_read_b128 v[208:211], v192 offset:38912
	ds_read_b128 v[212:215], v192 offset:39936
	global_load_lds_dwordx4 v168, s[30:31]
	s_mov_b32 m0, s15
	s_nop 0
	global_load_lds_dwordx4 v164, s[30:31]
	s_add_u32 s30, s30, 0x100000
	s_addc_u32 s31, s31, 0
	s_mov_b32 m0, s52
	s_nop 0
	global_load_lds_dwordx4 v168, s[30:31]
	s_mov_b32 m0, s53
	s_nop 0
	global_load_lds_dwordx4 v164, s[30:31]
	s_waitcnt vmcnt(8)
	s_waitcnt lgkmcnt(0)
	s_barrier
	s_waitcnt lgkmcnt(0)
	v_mfma_f32_16x16x32_bf16 v[126:129], v[130:133], v[174:177], v[126:129]
	v_mfma_f32_16x16x32_bf16 v[126:129], v[134:137], v[180:183], v[126:129]
	v_mfma_f32_16x16x32_bf16 v[110:113], v[130:133], v[184:187], v[110:113]
	v_mfma_f32_16x16x32_bf16 v[110:113], v[134:137], v[188:191], v[110:113]
	v_mfma_f32_16x16x32_bf16 v[94:97], v[130:133], v[200:203], v[94:97]
	v_mfma_f32_16x16x32_bf16 v[94:97], v[134:137], v[204:207], v[94:97]
	v_mfma_f32_16x16x32_bf16 v[78:81], v[130:133], v[208:211], v[78:81]
	v_mfma_f32_16x16x32_bf16 v[78:81], v[134:137], v[212:215], v[78:81]
	v_mfma_f32_16x16x32_bf16 v[122:125], v[138:141], v[174:177], v[122:125]
	v_mfma_f32_16x16x32_bf16 v[122:125], v[142:145], v[180:183], v[122:125]
	v_mfma_f32_16x16x32_bf16 v[106:109], v[138:141], v[184:187], v[106:109]
	v_mfma_f32_16x16x32_bf16 v[106:109], v[142:145], v[188:191], v[106:109]
	v_mfma_f32_16x16x32_bf16 v[90:93], v[138:141], v[200:203], v[90:93]
	v_mfma_f32_16x16x32_bf16 v[90:93], v[142:145], v[204:207], v[90:93]
	v_mfma_f32_16x16x32_bf16 v[74:77], v[138:141], v[208:211], v[74:77]
	v_mfma_f32_16x16x32_bf16 v[74:77], v[142:145], v[212:215], v[74:77]
	v_mfma_f32_16x16x32_bf16 v[118:121], v[146:149], v[174:177], v[118:121]
	v_mfma_f32_16x16x32_bf16 v[118:121], v[150:153], v[180:183], v[118:121]
	v_mfma_f32_16x16x32_bf16 v[102:105], v[146:149], v[184:187], v[102:105]
	v_mfma_f32_16x16x32_bf16 v[102:105], v[150:153], v[188:191], v[102:105]
	v_mfma_f32_16x16x32_bf16 v[86:89], v[146:149], v[200:203], v[86:89]
	v_mfma_f32_16x16x32_bf16 v[86:89], v[150:153], v[204:207], v[86:89]
	v_mfma_f32_16x16x32_bf16 v[70:73], v[146:149], v[208:211], v[70:73]
	v_mfma_f32_16x16x32_bf16 v[70:73], v[150:153], v[212:215], v[70:73]
	v_mfma_f32_16x16x32_bf16 v[114:117], v[154:157], v[174:177], v[114:117]
	v_mfma_f32_16x16x32_bf16 v[114:117], v[158:161], v[180:183], v[114:117]
	v_mfma_f32_16x16x32_bf16 v[98:101], v[154:157], v[184:187], v[98:101]
	v_mfma_f32_16x16x32_bf16 v[98:101], v[158:161], v[188:191], v[98:101]
	v_mfma_f32_16x16x32_bf16 v[82:85], v[154:157], v[200:203], v[82:85]
	v_mfma_f32_16x16x32_bf16 v[82:85], v[158:161], v[204:207], v[82:85]
	v_mfma_f32_16x16x32_bf16 v[66:69], v[154:157], v[208:211], v[66:69]
	v_mfma_f32_16x16x32_bf16 v[66:69], v[158:161], v[212:215], v[66:69]
	s_barrier
	s_add_u32 s98, s28, 0x80
	s_addc_u32 s99, s29, 0
	s_add_i32 s30, s51, s9
	s_mov_b32 m0, s30
	ds_read_b128 v[174:177], v192 offset:49152
	ds_read_b128 v[180:183], v192 offset:50176
	ds_read_b128 v[184:187], v192 offset:51200
	ds_read_b128 v[188:191], v192 offset:52224
	ds_read_b128 v[200:203], v192 offset:53248
	ds_read_b128 v[204:207], v192 offset:54272
	ds_read_b128 v[208:211], v192 offset:55296
	ds_read_b128 v[212:215], v192 offset:56320
	global_load_lds_dwordx4 v166, s[98:99]
	s_add_i32 m0, s30, 0x2000
	s_add_u32 s28, s28, 0x100080
	s_addc_u32 s29, s29, 0
	s_add_i32 s30, s77, s9
	global_load_lds_dwordx4 v162, s[98:99]
	s_mov_b32 m0, s30
	s_nop 0
	global_load_lds_dwordx4 v166, s[28:29]
	s_add_i32 m0, s30, 0x2000
	s_nop 0
	global_load_lds_dwordx4 v162, s[28:29]
	s_waitcnt vmcnt(6)
	s_waitcnt lgkmcnt(0)
	s_barrier
	s_waitcnt lgkmcnt(0)
	v_mfma_f32_16x16x32_bf16 v[62:65], v[130:133], v[174:177], v[62:65]
	v_mfma_f32_16x16x32_bf16 v[62:65], v[134:137], v[180:183], v[62:65]
	v_mfma_f32_16x16x32_bf16 v[46:49], v[130:133], v[184:187], v[46:49]
	v_mfma_f32_16x16x32_bf16 v[46:49], v[134:137], v[188:191], v[46:49]
	v_mfma_f32_16x16x32_bf16 v[30:33], v[130:133], v[200:203], v[30:33]
	v_mfma_f32_16x16x32_bf16 v[30:33], v[134:137], v[204:207], v[30:33]
	v_mfma_f32_16x16x32_bf16 v[14:17], v[130:133], v[208:211], v[14:17]
	v_mfma_f32_16x16x32_bf16 v[14:17], v[134:137], v[212:215], v[14:17]
	v_mfma_f32_16x16x32_bf16 v[58:61], v[138:141], v[174:177], v[58:61]
	v_mfma_f32_16x16x32_bf16 v[58:61], v[142:145], v[180:183], v[58:61]
	v_mfma_f32_16x16x32_bf16 v[42:45], v[138:141], v[184:187], v[42:45]
	v_mfma_f32_16x16x32_bf16 v[42:45], v[142:145], v[188:191], v[42:45]
	v_mfma_f32_16x16x32_bf16 v[26:29], v[138:141], v[200:203], v[26:29]
	v_mfma_f32_16x16x32_bf16 v[26:29], v[142:145], v[204:207], v[26:29]
	v_mfma_f32_16x16x32_bf16 v[10:13], v[138:141], v[208:211], v[10:13]
	v_mfma_f32_16x16x32_bf16 v[10:13], v[142:145], v[212:215], v[10:13]
	v_mfma_f32_16x16x32_bf16 v[54:57], v[146:149], v[174:177], v[54:57]
	v_mfma_f32_16x16x32_bf16 v[54:57], v[150:153], v[180:183], v[54:57]
	v_mfma_f32_16x16x32_bf16 v[38:41], v[146:149], v[184:187], v[38:41]
	v_mfma_f32_16x16x32_bf16 v[38:41], v[150:153], v[188:191], v[38:41]
	v_mfma_f32_16x16x32_bf16 v[22:25], v[146:149], v[200:203], v[22:25]
	v_mfma_f32_16x16x32_bf16 v[22:25], v[150:153], v[204:207], v[22:25]
	v_mfma_f32_16x16x32_bf16 v[6:9], v[146:149], v[208:211], v[6:9]
	v_mfma_f32_16x16x32_bf16 v[6:9], v[150:153], v[212:215], v[6:9]
	v_mfma_f32_16x16x32_bf16 v[50:53], v[154:157], v[174:177], v[50:53]
	v_mfma_f32_16x16x32_bf16 v[50:53], v[158:161], v[180:183], v[50:53]
	v_mfma_f32_16x16x32_bf16 v[34:37], v[154:157], v[184:187], v[34:37]
	v_mfma_f32_16x16x32_bf16 v[34:37], v[158:161], v[188:191], v[34:37]
	v_mfma_f32_16x16x32_bf16 v[18:21], v[154:157], v[200:203], v[18:21]
	v_mfma_f32_16x16x32_bf16 v[18:21], v[158:161], v[204:207], v[18:21]
	v_mfma_f32_16x16x32_bf16 v[2:5], v[154:157], v[208:211], v[2:5]
	v_mfma_f32_16x16x32_bf16 v[2:5], v[158:161], v[212:215], v[2:5]
	s_barrier
	s_add_i32 s50, s50, 2
	s_add_u32 s0, s0, 0x100
	s_addc_u32 s1, s1, 0
	s_add_u32 s41, s41, 0x100
	s_addc_u32 s43, s43, 0
	s_cmp_gt_u32 s50, 61
	s_cbranch_scc0 .LBB0_230
	s_and_b64 vcc, exec, s[22:23]
	s_cbranch_vccz .LBB0_233
	s_barrier

.LBB0_577:
	s_add_u32 s98, s30, 0xfff80000
	s_addc_u32 s99, s31, -1
	s_add_u32 s34, s30, 0xfff80080
	s_addc_u32 s35, s31, -1
	s_add_i32 s66, 0, 0x10000
	s_cmp_eq_u32 s57, 28
	s_cselect_b32 s43, s19, s35
	s_cselect_b32 s42, s23, s34
	v_add_u32_e32 v0, s66, v228
	s_cselect_b32 s35, s25, s56
	s_cselect_b32 s34, s54, s55
	s_add_i32 s73, 0, 0x14000
	ds_read_b128 v[132:135], v0
	ds_read_b128 v[136:139], v0 offset:1024
	ds_read_b128 v[140:143], v0 offset:2048
	ds_read_b128 v[144:147], v0 offset:3072
	v_add_u32_e32 v0, s73, v228
	ds_read_b128 v[148:151], v0
	ds_read_b128 v[152:155], v0 offset:1024
	ds_read_b128 v[156:159], v0 offset:2048
	ds_read_b128 v[160:163], v0 offset:3072
	s_mov_b32 m0, s50
	ds_read_b128 v[164:167], v230
	ds_read_b128 v[168:171], v230 offset:1024
	ds_read_b128 v[172:175], v230 offset:2048
	ds_read_b128 v[176:179], v230 offset:3072
	ds_read_b128 v[180:183], v230 offset:4096
	ds_read_b128 v[184:187], v230 offset:5120
	ds_read_b128 v[188:191], v230 offset:6144
	ds_read_b128 v[192:195], v230 offset:7168
	global_load_lds_dwordx4 v206, s[98:99]
	s_mov_b32 m0, s51
	s_nop 0
	global_load_lds_dwordx4 v202, s[98:99]
	s_add_i32 m0, s46, 0xc000
	s_nop 0
	global_load_lds_dwordx4 v208, s[30:31]
	s_add_i32 m0, s46, 0xe000
	s_nop 0
	global_load_lds_dwordx4 v210, s[30:31]
	s_waitcnt vmcnt(8)
	s_waitcnt lgkmcnt(0)
	s_barrier
	s_waitcnt lgkmcnt(0)
	v_mfma_f32_16x16x32_bf16 v[128:131], v[132:135], v[164:167], v[128:131]
	v_mfma_f32_16x16x32_bf16 v[128:131], v[136:139], v[168:171], v[128:131]
	v_mfma_f32_16x16x32_bf16 v[120:123], v[132:135], v[172:175], v[120:123]
	v_mfma_f32_16x16x32_bf16 v[120:123], v[136:139], v[176:179], v[120:123]
	v_mfma_f32_16x16x32_bf16 v[112:115], v[132:135], v[180:183], v[112:115]
	v_mfma_f32_16x16x32_bf16 v[112:115], v[136:139], v[184:187], v[112:115]
	v_mfma_f32_16x16x32_bf16 v[104:107], v[132:135], v[188:191], v[104:107]
	v_mfma_f32_16x16x32_bf16 v[104:107], v[136:139], v[192:195], v[104:107]
	v_mfma_f32_16x16x32_bf16 v[124:127], v[140:143], v[164:167], v[124:127]
	v_mfma_f32_16x16x32_bf16 v[124:127], v[144:147], v[168:171], v[124:127]
	v_mfma_f32_16x16x32_bf16 v[116:119], v[140:143], v[172:175], v[116:119]
	v_mfma_f32_16x16x32_bf16 v[116:119], v[144:147], v[176:179], v[116:119]
	v_mfma_f32_16x16x32_bf16 v[108:111], v[140:143], v[180:183], v[108:111]
	v_mfma_f32_16x16x32_bf16 v[108:111], v[144:147], v[184:187], v[108:111]
	v_mfma_f32_16x16x32_bf16 v[100:103], v[140:143], v[188:191], v[100:103]
	v_mfma_f32_16x16x32_bf16 v[100:103], v[144:147], v[192:195], v[100:103]
	v_mfma_f32_16x16x32_bf16 v[96:99], v[148:151], v[164:167], v[96:99]
	v_mfma_f32_16x16x32_bf16 v[96:99], v[152:155], v[168:171], v[96:99]
	v_mfma_f32_16x16x32_bf16 v[88:91], v[148:151], v[172:175], v[88:91]
	v_mfma_f32_16x16x32_bf16 v[88:91], v[152:155], v[176:179], v[88:91]
	v_mfma_f32_16x16x32_bf16 v[80:83], v[148:151], v[180:183], v[80:83]
	v_mfma_f32_16x16x32_bf16 v[80:83], v[152:155], v[184:187], v[80:83]
	v_mfma_f32_16x16x32_bf16 v[72:75], v[148:151], v[188:191], v[72:75]
	v_mfma_f32_16x16x32_bf16 v[72:75], v[152:155], v[192:195], v[72:75]
	v_mfma_f32_16x16x32_bf16 v[92:95], v[156:159], v[164:167], v[92:95]
	v_mfma_f32_16x16x32_bf16 v[92:95], v[160:163], v[168:171], v[92:95]
	v_mfma_f32_16x16x32_bf16 v[84:87], v[156:159], v[172:175], v[84:87]
	v_mfma_f32_16x16x32_bf16 v[84:87], v[160:163], v[176:179], v[84:87]
	v_mfma_f32_16x16x32_bf16 v[76:79], v[156:159], v[180:183], v[76:79]
	v_mfma_f32_16x16x32_bf16 v[76:79], v[160:163], v[184:187], v[76:79]
	v_mfma_f32_16x16x32_bf16 v[68:71], v[156:159], v[188:191], v[68:71]
	v_mfma_f32_16x16x32_bf16 v[68:71], v[160:163], v[192:195], v[68:71]
	s_barrier
	s_add_i32 s66, s66, s15
	s_mov_b32 m0, s66
	ds_read_b128 v[164:167], v230 offset:16384
	ds_read_b128 v[168:171], v230 offset:17408
	ds_read_b128 v[172:175], v230 offset:18432
	ds_read_b128 v[176:179], v230 offset:19456
	ds_read_b128 v[180:183], v230 offset:20480
	ds_read_b128 v[184:187], v230 offset:21504
	ds_read_b128 v[188:191], v230 offset:22528
	ds_read_b128 v[192:195], v230 offset:23552
	global_load_lds_dwordx4 v204, s[34:35]
	s_add_i32 m0, s66, 0x2000
	s_add_u32 s66, s34, 0x80000
	s_addc_u32 s67, s35, 0
	s_add_i32 s73, s73, s15
	global_load_lds_dwordx4 v200, s[34:35]
	s_mov_b32 m0, s73
	s_nop 0
	global_load_lds_dwordx4 v204, s[66:67]
	s_add_i32 m0, s73, 0x2000
	s_nop 0
	global_load_lds_dwordx4 v200, s[66:67]
	s_waitcnt vmcnt(6)
	s_waitcnt lgkmcnt(0)
	s_barrier
	s_waitcnt lgkmcnt(0)
	v_mfma_f32_16x16x32_bf16 v[64:67], v[132:135], v[164:167], v[64:67]
	v_mfma_f32_16x16x32_bf16 v[64:67], v[136:139], v[168:171], v[64:67]
	v_mfma_f32_16x16x32_bf16 v[56:59], v[132:135], v[172:175], v[56:59]
	v_mfma_f32_16x16x32_bf16 v[56:59], v[136:139], v[176:179], v[56:59]
	v_mfma_f32_16x16x32_bf16 v[48:51], v[132:135], v[180:183], v[48:51]
	v_mfma_f32_16x16x32_bf16 v[48:51], v[136:139], v[184:187], v[48:51]
	v_mfma_f32_16x16x32_bf16 v[40:43], v[132:135], v[188:191], v[40:43]
	v_mfma_f32_16x16x32_bf16 v[40:43], v[136:139], v[192:195], v[40:43]
	v_mfma_f32_16x16x32_bf16 v[60:63], v[140:143], v[164:167], v[60:63]
	v_mfma_f32_16x16x32_bf16 v[60:63], v[144:147], v[168:171], v[60:63]
	v_mfma_f32_16x16x32_bf16 v[52:55], v[140:143], v[172:175], v[52:55]
	v_mfma_f32_16x16x32_bf16 v[52:55], v[144:147], v[176:179], v[52:55]
	v_mfma_f32_16x16x32_bf16 v[44:47], v[140:143], v[180:183], v[44:47]
	v_mfma_f32_16x16x32_bf16 v[44:47], v[144:147], v[184:187], v[44:47]
	v_mfma_f32_16x16x32_bf16 v[36:39], v[140:143], v[188:191], v[36:39]
	v_mfma_f32_16x16x32_bf16 v[36:39], v[144:147], v[192:195], v[36:39]
	v_mfma_f32_16x16x32_bf16 v[32:35], v[148:151], v[164:167], v[32:35]
	v_mfma_f32_16x16x32_bf16 v[32:35], v[152:155], v[168:171], v[32:35]
	v_mfma_f32_16x16x32_bf16 v[28:31], v[156:159], v[164:167], v[28:31]
	v_mfma_f32_16x16x32_bf16 v[28:31], v[160:163], v[168:171], v[28:31]
	v_mfma_f32_16x16x32_bf16 v[24:27], v[148:151], v[172:175], v[24:27]
	v_mfma_f32_16x16x32_bf16 v[24:27], v[152:155], v[176:179], v[24:27]
	v_mfma_f32_16x16x32_bf16 v[20:23], v[156:159], v[172:175], v[20:23]
	v_mfma_f32_16x16x32_bf16 v[20:23], v[160:163], v[176:179], v[20:23]
	v_mfma_f32_16x16x32_bf16 v[16:19], v[148:151], v[180:183], v[16:19]
	v_mfma_f32_16x16x32_bf16 v[16:19], v[152:155], v[184:187], v[16:19]
	v_mfma_f32_16x16x32_bf16 v[12:15], v[156:159], v[180:183], v[12:15]
	v_mfma_f32_16x16x32_bf16 v[12:15], v[160:163], v[184:187], v[12:15]
	v_mfma_f32_16x16x32_bf16 v[8:11], v[148:151], v[188:191], v[8:11]
	v_mfma_f32_16x16x32_bf16 v[8:11], v[152:155], v[192:195], v[8:11]
	v_mfma_f32_16x16x32_bf16 v[2:5], v[156:159], v[188:191], v[4:7]
	v_mfma_f32_16x16x32_bf16 v[2:5], v[160:163], v[192:195], v[2:5]
	s_barrier
	s_add_i32 s66, 0, 0x18000
	v_add_u32_e32 v0, s66, v228
	s_add_i32 s67, 0, 0x1c000
	ds_read_b128 v[132:135], v0
	ds_read_b128 v[136:139], v0 offset:1024
	ds_read_b128 v[140:143], v0 offset:2048
	ds_read_b128 v[144:147], v0 offset:3072
	v_add_u32_e32 v0, s67, v228
	ds_read_b128 v[148:151], v0
	ds_read_b128 v[152:155], v0 offset:1024
	ds_read_b128 v[156:159], v0 offset:2048
	ds_read_b128 v[160:163], v0 offset:3072
	s_mov_b32 m0, s46
	ds_read_b128 v[164:167], v230 offset:32768
	ds_read_b128 v[168:171], v230 offset:33792
	ds_read_b128 v[172:175], v230 offset:34816
	ds_read_b128 v[176:179], v230 offset:35840
	ds_read_b128 v[180:183], v230 offset:36864
	ds_read_b128 v[184:187], v230 offset:37888
	ds_read_b128 v[188:191], v230 offset:38912
	ds_read_b128 v[192:195], v230 offset:39936
	global_load_lds_dwordx4 v206, s[42:43]
	s_mov_b32 m0, s47
	s_nop 0
	global_load_lds_dwordx4 v202, s[42:43]
	s_add_u32 s42, s42, 0x80000
	s_addc_u32 s43, s43, 0
	s_mov_b32 m0, s48
	s_nop 0
	global_load_lds_dwordx4 v206, s[42:43]
	s_mov_b32 m0, s49
	s_nop 0
	global_load_lds_dwordx4 v202, s[42:43]
	s_waitcnt vmcnt(8)
	s_waitcnt lgkmcnt(0)
	s_barrier
	s_waitcnt lgkmcnt(0)
	v_mfma_f32_16x16x32_bf16 v[128:131], v[132:135], v[164:167], v[128:131]
	v_mfma_f32_16x16x32_bf16 v[128:131], v[136:139], v[168:171], v[128:131]
	v_mfma_f32_16x16x32_bf16 v[120:123], v[132:135], v[172:175], v[120:123]
	v_mfma_f32_16x16x32_bf16 v[120:123], v[136:139], v[176:179], v[120:123]
	v_mfma_f32_16x16x32_bf16 v[112:115], v[132:135], v[180:183], v[112:115]
	v_mfma_f32_16x16x32_bf16 v[112:115], v[136:139], v[184:187], v[112:115]
	v_mfma_f32_16x16x32_bf16 v[104:107], v[132:135], v[188:191], v[104:107]
	v_mfma_f32_16x16x32_bf16 v[104:107], v[136:139], v[192:195], v[104:107]
	v_mfma_f32_16x16x32_bf16 v[124:127], v[140:143], v[164:167], v[124:127]
	v_mfma_f32_16x16x32_bf16 v[124:127], v[144:147], v[168:171], v[124:127]
	v_mfma_f32_16x16x32_bf16 v[116:119], v[140:143], v[172:175], v[116:119]
	v_mfma_f32_16x16x32_bf16 v[116:119], v[144:147], v[176:179], v[116:119]
	v_mfma_f32_16x16x32_bf16 v[108:111], v[140:143], v[180:183], v[108:111]
	v_mfma_f32_16x16x32_bf16 v[108:111], v[144:147], v[184:187], v[108:111]
	v_mfma_f32_16x16x32_bf16 v[100:103], v[140:143], v[188:191], v[100:103]
	v_mfma_f32_16x16x32_bf16 v[100:103], v[144:147], v[192:195], v[100:103]
	v_mfma_f32_16x16x32_bf16 v[96:99], v[148:151], v[164:167], v[96:99]
	v_mfma_f32_16x16x32_bf16 v[96:99], v[152:155], v[168:171], v[96:99]
	v_mfma_f32_16x16x32_bf16 v[88:91], v[148:151], v[172:175], v[88:91]
	v_mfma_f32_16x16x32_bf16 v[88:91], v[152:155], v[176:179], v[88:91]
	v_mfma_f32_16x16x32_bf16 v[80:83], v[148:151], v[180:183], v[80:83]
	v_mfma_f32_16x16x32_bf16 v[80:83], v[152:155], v[184:187], v[80:83]
	v_mfma_f32_16x16x32_bf16 v[72:75], v[148:151], v[188:191], v[72:75]
	v_mfma_f32_16x16x32_bf16 v[72:75], v[152:155], v[192:195], v[72:75]
	v_mfma_f32_16x16x32_bf16 v[92:95], v[156:159], v[164:167], v[92:95]
	v_mfma_f32_16x16x32_bf16 v[92:95], v[160:163], v[168:171], v[92:95]
	v_mfma_f32_16x16x32_bf16 v[84:87], v[156:159], v[172:175], v[84:87]
	v_mfma_f32_16x16x32_bf16 v[84:87], v[160:163], v[176:179], v[84:87]
	v_mfma_f32_16x16x32_bf16 v[76:79], v[156:159], v[180:183], v[76:79]
	v_mfma_f32_16x16x32_bf16 v[76:79], v[160:163], v[184:187], v[76:79]
	v_mfma_f32_16x16x32_bf16 v[68:71], v[156:159], v[188:191], v[68:71]
	v_mfma_f32_16x16x32_bf16 v[68:71], v[160:163], v[192:195], v[68:71]
	s_barrier
	s_add_i32 s42, s66, s15
	s_add_u32 s98, s34, 0x80
	s_addc_u32 s99, s35, 0
	s_mov_b32 m0, s42
	ds_read_b128 v[164:167], v230 offset:49152
	ds_read_b128 v[168:171], v230 offset:50176
	ds_read_b128 v[172:175], v230 offset:51200
	ds_read_b128 v[176:179], v230 offset:52224
	ds_read_b128 v[180:183], v230 offset:53248
	ds_read_b128 v[184:187], v230 offset:54272
	ds_read_b128 v[188:191], v230 offset:55296
	ds_read_b128 v[192:195], v230 offset:56320
	global_load_lds_dwordx4 v204, s[98:99]
	s_add_i32 m0, s42, 0x2000
	s_add_u32 s34, s34, 0x80080
	s_addc_u32 s35, s35, 0
	s_add_i32 s42, s67, s15
	global_load_lds_dwordx4 v200, s[98:99]
	s_mov_b32 m0, s42
	s_nop 0
	global_load_lds_dwordx4 v204, s[34:35]
	s_add_i32 m0, s42, 0x2000
	s_nop 0
	global_load_lds_dwordx4 v200, s[34:35]
	s_waitcnt vmcnt(6)
	s_waitcnt lgkmcnt(0)
	s_barrier
	s_waitcnt lgkmcnt(0)
	v_mfma_f32_16x16x32_bf16 v[64:67], v[132:135], v[164:167], v[64:67]
	v_mfma_f32_16x16x32_bf16 v[64:67], v[136:139], v[168:171], v[64:67]
	v_mfma_f32_16x16x32_bf16 v[56:59], v[132:135], v[172:175], v[56:59]
	v_mfma_f32_16x16x32_bf16 v[56:59], v[136:139], v[176:179], v[56:59]
	v_mfma_f32_16x16x32_bf16 v[48:51], v[132:135], v[180:183], v[48:51]
	v_mfma_f32_16x16x32_bf16 v[48:51], v[136:139], v[184:187], v[48:51]
	v_mfma_f32_16x16x32_bf16 v[40:43], v[132:135], v[188:191], v[40:43]
	v_mfma_f32_16x16x32_bf16 v[40:43], v[136:139], v[192:195], v[40:43]
	v_mfma_f32_16x16x32_bf16 v[60:63], v[140:143], v[164:167], v[60:63]
	v_mfma_f32_16x16x32_bf16 v[60:63], v[144:147], v[168:171], v[60:63]
	v_mfma_f32_16x16x32_bf16 v[52:55], v[140:143], v[172:175], v[52:55]
	v_mfma_f32_16x16x32_bf16 v[52:55], v[144:147], v[176:179], v[52:55]
	v_mfma_f32_16x16x32_bf16 v[44:47], v[140:143], v[180:183], v[44:47]
	v_mfma_f32_16x16x32_bf16 v[44:47], v[144:147], v[184:187], v[44:47]
	v_mfma_f32_16x16x32_bf16 v[36:39], v[140:143], v[188:191], v[36:39]
	v_mfma_f32_16x16x32_bf16 v[36:39], v[144:147], v[192:195], v[36:39]
	v_mfma_f32_16x16x32_bf16 v[32:35], v[148:151], v[164:167], v[32:35]
	v_mfma_f32_16x16x32_bf16 v[32:35], v[152:155], v[168:171], v[32:35]
	v_mfma_f32_16x16x32_bf16 v[28:31], v[156:159], v[164:167], v[28:31]
	v_mfma_f32_16x16x32_bf16 v[28:31], v[160:163], v[168:171], v[28:31]
	v_mfma_f32_16x16x32_bf16 v[24:27], v[148:151], v[172:175], v[24:27]
	v_mfma_f32_16x16x32_bf16 v[24:27], v[152:155], v[176:179], v[24:27]
	v_mfma_f32_16x16x32_bf16 v[20:23], v[156:159], v[172:175], v[20:23]
	v_mfma_f32_16x16x32_bf16 v[20:23], v[160:163], v[176:179], v[20:23]
	v_mfma_f32_16x16x32_bf16 v[16:19], v[148:151], v[180:183], v[16:19]
	v_mfma_f32_16x16x32_bf16 v[16:19], v[152:155], v[184:187], v[16:19]
	v_mfma_f32_16x16x32_bf16 v[12:15], v[156:159], v[180:183], v[12:15]
	v_mfma_f32_16x16x32_bf16 v[12:15], v[160:163], v[184:187], v[12:15]
	v_mfma_f32_16x16x32_bf16 v[6:9], v[148:151], v[188:191], v[8:11]
	v_mfma_f32_16x16x32_bf16 v[8:11], v[152:155], v[192:195], v[6:9]
	v_mfma_f32_16x16x32_bf16 v[2:5], v[156:159], v[188:191], v[2:5]
	v_mfma_f32_16x16x32_bf16 v[4:7], v[160:163], v[192:195], v[2:5]
	s_barrier
	s_add_i32 s57, s57, 2
	s_add_u32 s30, s30, 0x100
	s_addc_u32 s31, s31, 0
	s_add_u32 s55, s55, 0x100
	s_addc_u32 s56, s56, 0
	s_cmp_gt_u32 s57, 29
	s_cbranch_scc0 .LBB0_577
	s_and_b64 vcc, exec, s[20:21]
	s_cbranch_vccz .LBB0_580
	s_barrier

.LBB0_779:
	s_add_u32 s98, s30, 0xfff80000
	s_addc_u32 s99, s31, -1
	s_add_u32 s34, s30, 0xfff80080
	s_addc_u32 s35, s31, -1
	s_add_i32 s66, 0, 0x10000
	s_cmp_eq_u32 s57, 28
	s_cselect_b32 s43, s25, s35
	s_cselect_b32 s42, s53, s34
	s_cselect_b32 s35, s23, s56
	s_cselect_b32 s34, s54, s55
	s_add_i32 s73, 0, 0x14000
	v_add_u32_e32 v114, s66, v157
	v_add_u32_e32 v156, s73, v157
	ds_read_b128 v[90:93], v114
	ds_read_b128 v[94:97], v114 offset:1024
	ds_read_b128 v[106:109], v114 offset:2048
	ds_read_b128 v[114:117], v114 offset:3072
	ds_read_b128 v[162:165], v156
	ds_read_b128 v[166:169], v156 offset:1024
	ds_read_b128 v[170:173], v156 offset:2048
	ds_read_b128 v[174:177], v156 offset:3072
	s_mov_b32 m0, s50
	ds_read_b128 v[178:181], v161
	ds_read_b128 v[182:185], v161 offset:1024
	ds_read_b128 v[186:189], v161 offset:2048
	ds_read_b128 v[190:193], v161 offset:3072
	ds_read_b128 v[200:203], v161 offset:4096
	ds_read_b128 v[204:207], v161 offset:5120
	ds_read_b128 v[208:211], v161 offset:6144
	ds_read_b128 v[212:215], v161 offset:7168
	global_load_lds_dwordx4 v150, s[98:99]
	s_mov_b32 m0, s51
	s_nop 0
	global_load_lds_dwordx4 v148, s[98:99]
	s_add_i32 m0, s14, 0xc000
	s_nop 0
	global_load_lds_dwordx4 v152, s[30:31]
	s_add_i32 m0, s14, 0xe000
	s_nop 0
	global_load_lds_dwordx4 v154, s[30:31]
	s_waitcnt vmcnt(8)
	s_waitcnt lgkmcnt(0)
	s_barrier
	s_waitcnt lgkmcnt(0)
	v_mfma_i32_16x16x64_i8 v[142:145], v[90:93], v[178:181], v[142:145]
	v_mfma_i32_16x16x64_i8 v[142:145], v[94:97], v[182:185], v[142:145]
	v_mfma_i32_16x16x64_i8 v[126:129], v[90:93], v[186:189], v[126:129]
	v_mfma_i32_16x16x64_i8 v[126:129], v[94:97], v[190:193], v[126:129]
	v_mfma_i32_16x16x64_i8 v[102:105], v[90:93], v[200:203], v[102:105]
	v_mfma_i32_16x16x64_i8 v[102:105], v[94:97], v[204:207], v[102:105]
	v_mfma_i32_16x16x64_i8 v[78:81], v[90:93], v[208:211], v[78:81]
	v_mfma_i32_16x16x64_i8 v[78:81], v[94:97], v[212:215], v[78:81]
	v_mfma_i32_16x16x64_i8 v[138:141], v[106:109], v[178:181], v[138:141]
	v_mfma_i32_16x16x64_i8 v[138:141], v[114:117], v[182:185], v[138:141]
	v_mfma_i32_16x16x64_i8 v[122:125], v[106:109], v[186:189], v[122:125]
	v_mfma_i32_16x16x64_i8 v[122:125], v[114:117], v[190:193], v[122:125]
	v_mfma_i32_16x16x64_i8 v[98:101], v[106:109], v[200:203], v[98:101]
	v_mfma_i32_16x16x64_i8 v[98:101], v[114:117], v[204:207], v[98:101]
	v_mfma_i32_16x16x64_i8 v[74:77], v[106:109], v[208:211], v[74:77]
	v_mfma_i32_16x16x64_i8 v[74:77], v[114:117], v[212:215], v[74:77]
	v_mfma_i32_16x16x64_i8 v[134:137], v[162:165], v[178:181], v[134:137]
	v_mfma_i32_16x16x64_i8 v[134:137], v[166:169], v[182:185], v[134:137]
	v_mfma_i32_16x16x64_i8 v[118:121], v[162:165], v[186:189], v[118:121]
	v_mfma_i32_16x16x64_i8 v[118:121], v[166:169], v[190:193], v[118:121]
	v_mfma_i32_16x16x64_i8 v[86:89], v[162:165], v[200:203], v[86:89]
	v_mfma_i32_16x16x64_i8 v[86:89], v[166:169], v[204:207], v[86:89]
	v_mfma_i32_16x16x64_i8 v[70:73], v[162:165], v[208:211], v[70:73]
	v_mfma_i32_16x16x64_i8 v[70:73], v[166:169], v[212:215], v[70:73]
	v_mfma_i32_16x16x64_i8 v[130:133], v[170:173], v[178:181], v[130:133]
	v_mfma_i32_16x16x64_i8 v[130:133], v[174:177], v[182:185], v[130:133]
	v_mfma_i32_16x16x64_i8 v[110:113], v[170:173], v[186:189], v[110:113]
	v_mfma_i32_16x16x64_i8 v[110:113], v[174:177], v[190:193], v[110:113]
	v_mfma_i32_16x16x64_i8 v[82:85], v[170:173], v[200:203], v[82:85]
	v_mfma_i32_16x16x64_i8 v[82:85], v[174:177], v[204:207], v[82:85]
	v_mfma_i32_16x16x64_i8 v[66:69], v[170:173], v[208:211], v[66:69]
	v_mfma_i32_16x16x64_i8 v[66:69], v[174:177], v[212:215], v[66:69]
	s_barrier
	s_add_i32 s66, s66, s9
	s_mov_b32 m0, s66
	ds_read_b128 v[178:181], v161 offset:16384
	ds_read_b128 v[182:185], v161 offset:17408
	ds_read_b128 v[186:189], v161 offset:18432
	ds_read_b128 v[190:193], v161 offset:19456
	ds_read_b128 v[200:203], v161 offset:20480
	ds_read_b128 v[204:207], v161 offset:21504
	ds_read_b128 v[208:211], v161 offset:22528
	ds_read_b128 v[212:215], v161 offset:23552
	global_load_lds_dwordx4 v0, s[34:35]
	s_add_i32 m0, s66, 0x2000
	s_add_u32 s66, s34, 0x80000
	s_addc_u32 s67, s35, 0
	s_add_i32 s73, s73, s9
	global_load_lds_dwordx4 v146, s[34:35]
	s_mov_b32 m0, s73
	s_nop 0
	global_load_lds_dwordx4 v0, s[66:67]
	s_add_i32 m0, s73, 0x2000
	s_nop 0
	global_load_lds_dwordx4 v146, s[66:67]
	s_waitcnt vmcnt(6)
	s_waitcnt lgkmcnt(0)
	s_barrier
	s_waitcnt lgkmcnt(0)
	v_mfma_i32_16x16x64_i8 v[62:65], v[90:93], v[178:181], v[62:65]
	v_mfma_i32_16x16x64_i8 v[62:65], v[94:97], v[182:185], v[62:65]
	v_mfma_i32_16x16x64_i8 v[46:49], v[90:93], v[186:189], v[46:49]
	v_mfma_i32_16x16x64_i8 v[46:49], v[94:97], v[190:193], v[46:49]
	v_mfma_i32_16x16x64_i8 v[30:33], v[90:93], v[200:203], v[30:33]
	v_mfma_i32_16x16x64_i8 v[30:33], v[94:97], v[204:207], v[30:33]
	v_mfma_i32_16x16x64_i8 v[14:17], v[90:93], v[208:211], v[14:17]
	v_mfma_i32_16x16x64_i8 v[14:17], v[94:97], v[212:215], v[14:17]
	v_mfma_i32_16x16x64_i8 v[58:61], v[106:109], v[178:181], v[58:61]
	v_mfma_i32_16x16x64_i8 v[58:61], v[114:117], v[182:185], v[58:61]
	v_mfma_i32_16x16x64_i8 v[42:45], v[106:109], v[186:189], v[42:45]
	v_mfma_i32_16x16x64_i8 v[42:45], v[114:117], v[190:193], v[42:45]
	v_mfma_i32_16x16x64_i8 v[26:29], v[106:109], v[200:203], v[26:29]
	v_mfma_i32_16x16x64_i8 v[26:29], v[114:117], v[204:207], v[26:29]
	v_mfma_i32_16x16x64_i8 v[10:13], v[106:109], v[208:211], v[10:13]
	v_mfma_i32_16x16x64_i8 v[10:13], v[114:117], v[212:215], v[10:13]
	v_mfma_i32_16x16x64_i8 v[54:57], v[162:165], v[178:181], v[54:57]
	v_mfma_i32_16x16x64_i8 v[54:57], v[166:169], v[182:185], v[54:57]
	v_mfma_i32_16x16x64_i8 v[38:41], v[162:165], v[186:189], v[38:41]
	v_mfma_i32_16x16x64_i8 v[38:41], v[166:169], v[190:193], v[38:41]
	v_mfma_i32_16x16x64_i8 v[22:25], v[162:165], v[200:203], v[22:25]
	v_mfma_i32_16x16x64_i8 v[22:25], v[166:169], v[204:207], v[22:25]
	v_mfma_i32_16x16x64_i8 v[6:9], v[162:165], v[208:211], v[6:9]
	v_mfma_i32_16x16x64_i8 v[6:9], v[166:169], v[212:215], v[6:9]
	v_mfma_i32_16x16x64_i8 v[50:53], v[170:173], v[178:181], v[50:53]
	v_mfma_i32_16x16x64_i8 v[50:53], v[174:177], v[182:185], v[50:53]
	v_mfma_i32_16x16x64_i8 v[34:37], v[170:173], v[186:189], v[34:37]
	v_mfma_i32_16x16x64_i8 v[34:37], v[174:177], v[190:193], v[34:37]
	v_mfma_i32_16x16x64_i8 v[18:21], v[170:173], v[200:203], v[18:21]
	v_mfma_i32_16x16x64_i8 v[18:21], v[174:177], v[204:207], v[18:21]
	v_mfma_i32_16x16x64_i8 v[2:5], v[170:173], v[208:211], v[2:5]
	v_mfma_i32_16x16x64_i8 v[2:5], v[174:177], v[212:215], v[2:5]
	s_barrier
	s_add_i32 s66, 0, 0x18000
	s_add_i32 s67, 0, 0x1c000
	v_add_u32_e32 v114, s66, v157
	v_add_u32_e32 v156, s67, v157
	ds_read_b128 v[90:93], v114
	ds_read_b128 v[94:97], v114 offset:1024
	ds_read_b128 v[106:109], v114 offset:2048
	ds_read_b128 v[114:117], v114 offset:3072
	ds_read_b128 v[162:165], v156
	ds_read_b128 v[166:169], v156 offset:1024
	ds_read_b128 v[170:173], v156 offset:2048
	ds_read_b128 v[174:177], v156 offset:3072
	s_mov_b32 m0, s14
	ds_read_b128 v[178:181], v161 offset:32768
	ds_read_b128 v[182:185], v161 offset:33792
	ds_read_b128 v[186:189], v161 offset:34816
	ds_read_b128 v[190:193], v161 offset:35840
	ds_read_b128 v[200:203], v161 offset:36864
	ds_read_b128 v[204:207], v161 offset:37888
	ds_read_b128 v[208:211], v161 offset:38912
	ds_read_b128 v[212:215], v161 offset:39936
	global_load_lds_dwordx4 v150, s[42:43]
	s_mov_b32 m0, s15
	s_nop 0
	global_load_lds_dwordx4 v148, s[42:43]
	s_add_u32 s42, s42, 0x80000
	s_addc_u32 s43, s43, 0
	s_mov_b32 m0, s46
	s_nop 0
	global_load_lds_dwordx4 v150, s[42:43]
	s_mov_b32 m0, s47
	s_nop 0
	global_load_lds_dwordx4 v148, s[42:43]
	s_waitcnt vmcnt(8)
	s_waitcnt lgkmcnt(0)
	s_barrier
	s_waitcnt lgkmcnt(0)
	v_mfma_i32_16x16x64_i8 v[142:145], v[90:93], v[178:181], v[142:145]
	v_mfma_i32_16x16x64_i8 v[142:145], v[94:97], v[182:185], v[142:145]
	v_mfma_i32_16x16x64_i8 v[126:129], v[90:93], v[186:189], v[126:129]
	v_mfma_i32_16x16x64_i8 v[126:129], v[94:97], v[190:193], v[126:129]
	v_mfma_i32_16x16x64_i8 v[102:105], v[90:93], v[200:203], v[102:105]
	v_mfma_i32_16x16x64_i8 v[102:105], v[94:97], v[204:207], v[102:105]
	v_mfma_i32_16x16x64_i8 v[78:81], v[90:93], v[208:211], v[78:81]
	v_mfma_i32_16x16x64_i8 v[78:81], v[94:97], v[212:215], v[78:81]
	v_mfma_i32_16x16x64_i8 v[138:141], v[106:109], v[178:181], v[138:141]
	v_mfma_i32_16x16x64_i8 v[138:141], v[114:117], v[182:185], v[138:141]
	v_mfma_i32_16x16x64_i8 v[122:125], v[106:109], v[186:189], v[122:125]
	v_mfma_i32_16x16x64_i8 v[122:125], v[114:117], v[190:193], v[122:125]
	v_mfma_i32_16x16x64_i8 v[98:101], v[106:109], v[200:203], v[98:101]
	v_mfma_i32_16x16x64_i8 v[98:101], v[114:117], v[204:207], v[98:101]
	v_mfma_i32_16x16x64_i8 v[74:77], v[106:109], v[208:211], v[74:77]
	v_mfma_i32_16x16x64_i8 v[74:77], v[114:117], v[212:215], v[74:77]
	v_mfma_i32_16x16x64_i8 v[134:137], v[162:165], v[178:181], v[134:137]
	v_mfma_i32_16x16x64_i8 v[134:137], v[166:169], v[182:185], v[134:137]
	v_mfma_i32_16x16x64_i8 v[118:121], v[162:165], v[186:189], v[118:121]
	v_mfma_i32_16x16x64_i8 v[118:121], v[166:169], v[190:193], v[118:121]
	v_mfma_i32_16x16x64_i8 v[86:89], v[162:165], v[200:203], v[86:89]
	v_mfma_i32_16x16x64_i8 v[86:89], v[166:169], v[204:207], v[86:89]
	v_mfma_i32_16x16x64_i8 v[70:73], v[162:165], v[208:211], v[70:73]
	v_mfma_i32_16x16x64_i8 v[70:73], v[166:169], v[212:215], v[70:73]
	v_mfma_i32_16x16x64_i8 v[130:133], v[170:173], v[178:181], v[130:133]
	v_mfma_i32_16x16x64_i8 v[130:133], v[174:177], v[182:185], v[130:133]
	v_mfma_i32_16x16x64_i8 v[110:113], v[170:173], v[186:189], v[110:113]
	v_mfma_i32_16x16x64_i8 v[110:113], v[174:177], v[190:193], v[110:113]
	v_mfma_i32_16x16x64_i8 v[82:85], v[170:173], v[200:203], v[82:85]
	v_mfma_i32_16x16x64_i8 v[82:85], v[174:177], v[204:207], v[82:85]
	v_mfma_i32_16x16x64_i8 v[66:69], v[170:173], v[208:211], v[66:69]
	v_mfma_i32_16x16x64_i8 v[66:69], v[174:177], v[212:215], v[66:69]
	s_barrier
	s_add_u32 s98, s34, 0x80
	s_addc_u32 s99, s35, 0
	s_add_i32 s42, s66, s9
	s_mov_b32 m0, s42
	ds_read_b128 v[178:181], v161 offset:49152
	ds_read_b128 v[182:185], v161 offset:50176
	ds_read_b128 v[186:189], v161 offset:51200
	ds_read_b128 v[190:193], v161 offset:52224
	ds_read_b128 v[200:203], v161 offset:53248
	ds_read_b128 v[204:207], v161 offset:54272
	ds_read_b128 v[208:211], v161 offset:55296
	ds_read_b128 v[212:215], v161 offset:56320
	global_load_lds_dwordx4 v0, s[98:99]
	s_add_i32 m0, s42, 0x2000
	s_add_u32 s34, s34, 0x80080
	s_addc_u32 s35, s35, 0
	s_add_i32 s42, s67, s9
	global_load_lds_dwordx4 v146, s[98:99]
	s_mov_b32 m0, s42
	s_nop 0
	global_load_lds_dwordx4 v0, s[34:35]
	s_add_i32 m0, s42, 0x2000
	s_nop 0
	global_load_lds_dwordx4 v146, s[34:35]
	s_waitcnt vmcnt(6)
	s_waitcnt lgkmcnt(0)
	s_barrier
	s_waitcnt lgkmcnt(0)
	v_mfma_i32_16x16x64_i8 v[62:65], v[90:93], v[178:181], v[62:65]
	v_mfma_i32_16x16x64_i8 v[62:65], v[94:97], v[182:185], v[62:65]
	v_mfma_i32_16x16x64_i8 v[46:49], v[90:93], v[186:189], v[46:49]
	v_mfma_i32_16x16x64_i8 v[46:49], v[94:97], v[190:193], v[46:49]
	v_mfma_i32_16x16x64_i8 v[30:33], v[90:93], v[200:203], v[30:33]
	v_mfma_i32_16x16x64_i8 v[30:33], v[94:97], v[204:207], v[30:33]
	v_mfma_i32_16x16x64_i8 v[14:17], v[90:93], v[208:211], v[14:17]
	v_mfma_i32_16x16x64_i8 v[14:17], v[94:97], v[212:215], v[14:17]
	v_mfma_i32_16x16x64_i8 v[58:61], v[106:109], v[178:181], v[58:61]
	v_mfma_i32_16x16x64_i8 v[58:61], v[114:117], v[182:185], v[58:61]
	v_mfma_i32_16x16x64_i8 v[42:45], v[106:109], v[186:189], v[42:45]
	v_mfma_i32_16x16x64_i8 v[42:45], v[114:117], v[190:193], v[42:45]
	v_mfma_i32_16x16x64_i8 v[26:29], v[106:109], v[200:203], v[26:29]
	v_mfma_i32_16x16x64_i8 v[26:29], v[114:117], v[204:207], v[26:29]
	v_mfma_i32_16x16x64_i8 v[10:13], v[106:109], v[208:211], v[10:13]
	v_mfma_i32_16x16x64_i8 v[10:13], v[114:117], v[212:215], v[10:13]
	v_mfma_i32_16x16x64_i8 v[54:57], v[162:165], v[178:181], v[54:57]
	v_mfma_i32_16x16x64_i8 v[54:57], v[166:169], v[182:185], v[54:57]
	v_mfma_i32_16x16x64_i8 v[38:41], v[162:165], v[186:189], v[38:41]
	v_mfma_i32_16x16x64_i8 v[38:41], v[166:169], v[190:193], v[38:41]
	v_mfma_i32_16x16x64_i8 v[22:25], v[162:165], v[200:203], v[22:25]
	v_mfma_i32_16x16x64_i8 v[22:25], v[166:169], v[204:207], v[22:25]
	v_mfma_i32_16x16x64_i8 v[6:9], v[162:165], v[208:211], v[6:9]
	v_mfma_i32_16x16x64_i8 v[6:9], v[166:169], v[212:215], v[6:9]
	v_mfma_i32_16x16x64_i8 v[50:53], v[170:173], v[178:181], v[50:53]
	v_mfma_i32_16x16x64_i8 v[50:53], v[174:177], v[182:185], v[50:53]
	v_mfma_i32_16x16x64_i8 v[34:37], v[170:173], v[186:189], v[34:37]
	v_mfma_i32_16x16x64_i8 v[34:37], v[174:177], v[190:193], v[34:37]
	v_mfma_i32_16x16x64_i8 v[18:21], v[170:173], v[200:203], v[18:21]
	v_mfma_i32_16x16x64_i8 v[18:21], v[174:177], v[204:207], v[18:21]
	v_mfma_i32_16x16x64_i8 v[2:5], v[170:173], v[208:211], v[2:5]
	v_mfma_i32_16x16x64_i8 v[2:5], v[174:177], v[212:215], v[2:5]
	s_barrier
	s_add_i32 s57, s57, 2
	s_add_u32 s30, s30, 0x100
	s_addc_u32 s31, s31, 0
	s_add_u32 s55, s55, 0x100
	s_addc_u32 s56, s56, 0
	s_cmp_gt_u32 s57, 29
	s_cbranch_scc0 .LBB0_779
	s_and_b64 vcc, exec, s[20:21]
	s_mov_b32 s54, 0x5c401000
	s_cbranch_vccz .LBB0_782
	s_barrier

.LBB0_801:
	s_add_u32 s98, s30, 0xfff00000
	s_addc_u32 s99, s31, -1
	s_add_u32 s34, s30, 0xfff00080
	s_addc_u32 s35, s31, -1
	s_add_i32 s54, 0, 0x10000
	s_cmp_eq_u32 s53, 60
	s_cselect_b32 s41, s25, s35
	s_cselect_b32 s40, s49, s34
	s_cselect_b32 s35, s23, s52
	s_cselect_b32 s34, s50, s51
	s_add_i32 s56, 0, 0x14000
	v_add_u32_e32 v156, s54, v141
	v_add_u32_e32 v172, s56, v141
	ds_read_b128 v[144:147], v156
	ds_read_b128 v[148:151], v156 offset:1024
	ds_read_b128 v[152:155], v156 offset:2048
	ds_read_b128 v[156:159], v156 offset:3072
	ds_read_b128 v[160:163], v172
	ds_read_b128 v[164:167], v172 offset:1024
	ds_read_b128 v[168:171], v172 offset:2048
	ds_read_b128 v[172:175], v172 offset:3072
	s_mov_b32 m0, s42
	ds_read_b128 v[176:179], v143
	ds_read_b128 v[180:183], v143 offset:1024
	ds_read_b128 v[184:187], v143 offset:2048
	ds_read_b128 v[188:191], v143 offset:3072
	ds_read_b128 v[192:195], v143 offset:4096
	ds_read_b128 v[200:203], v143 offset:5120
	ds_read_b128 v[204:207], v143 offset:6144
	ds_read_b128 v[208:211], v143 offset:7168
	global_load_lds_dwordx4 v134, s[98:99]
	s_mov_b32 m0, s43
	s_nop 0
	global_load_lds_dwordx4 v132, s[98:99]
	s_add_i32 m0, s14, 0xc000
	s_nop 0
	global_load_lds_dwordx4 v136, s[30:31]
	s_add_i32 m0, s14, 0xe000
	s_nop 0
	global_load_lds_dwordx4 v138, s[30:31]
	s_waitcnt vmcnt(8)
	s_waitcnt lgkmcnt(0)
	s_barrier
	s_waitcnt lgkmcnt(0)
	v_mfma_f32_16x16x32_bf16 v[126:129], v[144:147], v[176:179], v[126:129]
	v_mfma_f32_16x16x32_bf16 v[126:129], v[148:151], v[180:183], v[126:129]
	v_mfma_f32_16x16x32_bf16 v[118:121], v[144:147], v[184:187], v[118:121]
	v_mfma_f32_16x16x32_bf16 v[118:121], v[148:151], v[188:191], v[118:121]
	v_mfma_f32_16x16x32_bf16 v[102:105], v[144:147], v[192:195], v[102:105]
	v_mfma_f32_16x16x32_bf16 v[102:105], v[148:151], v[200:203], v[102:105]
	v_mfma_f32_16x16x32_bf16 v[86:89], v[144:147], v[204:207], v[86:89]
	v_mfma_f32_16x16x32_bf16 v[86:89], v[148:151], v[208:211], v[86:89]
	v_mfma_f32_16x16x32_bf16 v[122:125], v[152:155], v[176:179], v[122:125]
	v_mfma_f32_16x16x32_bf16 v[122:125], v[156:159], v[180:183], v[122:125]
	v_mfma_f32_16x16x32_bf16 v[114:117], v[152:155], v[184:187], v[114:117]
	v_mfma_f32_16x16x32_bf16 v[114:117], v[156:159], v[188:191], v[114:117]
	v_mfma_f32_16x16x32_bf16 v[98:101], v[152:155], v[192:195], v[98:101]
	v_mfma_f32_16x16x32_bf16 v[98:101], v[156:159], v[200:203], v[98:101]
	v_mfma_f32_16x16x32_bf16 v[82:85], v[152:155], v[204:207], v[82:85]
	v_mfma_f32_16x16x32_bf16 v[82:85], v[156:159], v[208:211], v[82:85]
	v_mfma_f32_16x16x32_bf16 v[110:113], v[160:163], v[176:179], v[110:113]
	v_mfma_f32_16x16x32_bf16 v[110:113], v[164:167], v[180:183], v[110:113]
	v_mfma_f32_16x16x32_bf16 v[94:97], v[160:163], v[184:187], v[94:97]
	v_mfma_f32_16x16x32_bf16 v[94:97], v[164:167], v[188:191], v[94:97]
	v_mfma_f32_16x16x32_bf16 v[78:81], v[160:163], v[192:195], v[78:81]
	v_mfma_f32_16x16x32_bf16 v[78:81], v[164:167], v[200:203], v[78:81]
	v_mfma_f32_16x16x32_bf16 v[70:73], v[160:163], v[204:207], v[70:73]
	v_mfma_f32_16x16x32_bf16 v[70:73], v[164:167], v[208:211], v[70:73]
	v_mfma_f32_16x16x32_bf16 v[106:109], v[168:171], v[176:179], v[106:109]
	v_mfma_f32_16x16x32_bf16 v[106:109], v[172:175], v[180:183], v[106:109]
	v_mfma_f32_16x16x32_bf16 v[90:93], v[168:171], v[184:187], v[90:93]
	v_mfma_f32_16x16x32_bf16 v[90:93], v[172:175], v[188:191], v[90:93]
	v_mfma_f32_16x16x32_bf16 v[74:77], v[168:171], v[192:195], v[74:77]
	v_mfma_f32_16x16x32_bf16 v[74:77], v[172:175], v[200:203], v[74:77]
	v_mfma_f32_16x16x32_bf16 v[66:69], v[168:171], v[204:207], v[66:69]
	v_mfma_f32_16x16x32_bf16 v[66:69], v[172:175], v[208:211], v[66:69]
	s_barrier
	s_add_i32 s54, s54, s9
	s_mov_b32 m0, s54
	ds_read_b128 v[176:179], v143 offset:16384
	ds_read_b128 v[180:183], v143 offset:17408
	ds_read_b128 v[184:187], v143 offset:18432
	ds_read_b128 v[188:191], v143 offset:19456
	ds_read_b128 v[192:195], v143 offset:20480
	ds_read_b128 v[200:203], v143 offset:21504
	ds_read_b128 v[204:207], v143 offset:22528
	ds_read_b128 v[208:211], v143 offset:23552
	global_load_lds_dwordx4 v0, s[34:35]
	s_add_i32 m0, s54, 0x2000
	s_add_u32 s54, s34, 0x100000
	s_addc_u32 s55, s35, 0
	s_add_i32 s56, s56, s9
	global_load_lds_dwordx4 v130, s[34:35]
	s_mov_b32 m0, s56
	s_nop 0
	global_load_lds_dwordx4 v0, s[54:55]
	s_add_i32 m0, s56, 0x2000
	s_nop 0
	global_load_lds_dwordx4 v130, s[54:55]
	s_waitcnt vmcnt(6)
	s_waitcnt lgkmcnt(0)
	s_barrier
	s_waitcnt lgkmcnt(0)
	v_mfma_f32_16x16x32_bf16 v[62:65], v[144:147], v[176:179], v[62:65]
	v_mfma_f32_16x16x32_bf16 v[62:65], v[148:151], v[180:183], v[62:65]
	v_mfma_f32_16x16x32_bf16 v[54:57], v[144:147], v[184:187], v[54:57]
	v_mfma_f32_16x16x32_bf16 v[54:57], v[148:151], v[188:191], v[54:57]
	v_mfma_f32_16x16x32_bf16 v[38:41], v[144:147], v[192:195], v[38:41]
	v_mfma_f32_16x16x32_bf16 v[38:41], v[148:151], v[200:203], v[38:41]
	v_mfma_f32_16x16x32_bf16 v[22:25], v[144:147], v[204:207], v[22:25]
	v_mfma_f32_16x16x32_bf16 v[22:25], v[148:151], v[208:211], v[22:25]
	v_mfma_f32_16x16x32_bf16 v[58:61], v[152:155], v[176:179], v[58:61]
	v_mfma_f32_16x16x32_bf16 v[58:61], v[156:159], v[180:183], v[58:61]
	v_mfma_f32_16x16x32_bf16 v[50:53], v[152:155], v[184:187], v[50:53]
	v_mfma_f32_16x16x32_bf16 v[50:53], v[156:159], v[188:191], v[50:53]
	v_mfma_f32_16x16x32_bf16 v[34:37], v[152:155], v[192:195], v[34:37]
	v_mfma_f32_16x16x32_bf16 v[34:37], v[156:159], v[200:203], v[34:37]
	v_mfma_f32_16x16x32_bf16 v[18:21], v[152:155], v[204:207], v[18:21]
	v_mfma_f32_16x16x32_bf16 v[18:21], v[156:159], v[208:211], v[18:21]
	v_mfma_f32_16x16x32_bf16 v[46:49], v[160:163], v[176:179], v[46:49]
	v_mfma_f32_16x16x32_bf16 v[46:49], v[164:167], v[180:183], v[46:49]
	v_mfma_f32_16x16x32_bf16 v[30:33], v[160:163], v[184:187], v[30:33]
	v_mfma_f32_16x16x32_bf16 v[30:33], v[164:167], v[188:191], v[30:33]
	v_mfma_f32_16x16x32_bf16 v[14:17], v[160:163], v[192:195], v[14:17]
	v_mfma_f32_16x16x32_bf16 v[14:17], v[164:167], v[200:203], v[14:17]
	v_mfma_f32_16x16x32_bf16 v[6:9], v[160:163], v[204:207], v[6:9]
	v_mfma_f32_16x16x32_bf16 v[6:9], v[164:167], v[208:211], v[6:9]
	v_mfma_f32_16x16x32_bf16 v[42:45], v[168:171], v[176:179], v[42:45]
	v_mfma_f32_16x16x32_bf16 v[42:45], v[172:175], v[180:183], v[42:45]
	v_mfma_f32_16x16x32_bf16 v[26:29], v[168:171], v[184:187], v[26:29]
	v_mfma_f32_16x16x32_bf16 v[26:29], v[172:175], v[188:191], v[26:29]
	v_mfma_f32_16x16x32_bf16 v[10:13], v[168:171], v[192:195], v[10:13]
	v_mfma_f32_16x16x32_bf16 v[10:13], v[172:175], v[200:203], v[10:13]
	v_mfma_f32_16x16x32_bf16 v[2:5], v[168:171], v[204:207], v[2:5]
	v_mfma_f32_16x16x32_bf16 v[2:5], v[172:175], v[208:211], v[2:5]
	s_barrier
	s_add_i32 s54, 0, 0x18000
	s_add_i32 s55, 0, 0x1c000
	v_add_u32_e32 v156, s54, v141
	v_add_u32_e32 v172, s55, v141
	ds_read_b128 v[144:147], v156
	ds_read_b128 v[148:151], v156 offset:1024
	ds_read_b128 v[152:155], v156 offset:2048
	ds_read_b128 v[156:159], v156 offset:3072
	ds_read_b128 v[160:163], v172
	ds_read_b128 v[164:167], v172 offset:1024
	ds_read_b128 v[168:171], v172 offset:2048
	ds_read_b128 v[172:175], v172 offset:3072
	s_mov_b32 m0, s14
	ds_read_b128 v[176:179], v143 offset:32768
	ds_read_b128 v[180:183], v143 offset:33792
	ds_read_b128 v[184:187], v143 offset:34816
	ds_read_b128 v[188:191], v143 offset:35840
	ds_read_b128 v[192:195], v143 offset:36864
	ds_read_b128 v[200:203], v143 offset:37888
	ds_read_b128 v[204:207], v143 offset:38912
	ds_read_b128 v[208:211], v143 offset:39936
	global_load_lds_dwordx4 v134, s[40:41]
	s_mov_b32 m0, s15
	s_nop 0
	global_load_lds_dwordx4 v132, s[40:41]
	s_add_u32 s40, s40, 0x100000
	s_addc_u32 s41, s41, 0
	s_mov_b32 m0, s18
	s_nop 0
	global_load_lds_dwordx4 v134, s[40:41]
	s_mov_b32 m0, s19
	s_nop 0
	global_load_lds_dwordx4 v132, s[40:41]
	s_waitcnt vmcnt(8)
	s_waitcnt lgkmcnt(0)
	s_barrier
	s_waitcnt lgkmcnt(0)
	v_mfma_f32_16x16x32_bf16 v[126:129], v[144:147], v[176:179], v[126:129]
	v_mfma_f32_16x16x32_bf16 v[126:129], v[148:151], v[180:183], v[126:129]
	v_mfma_f32_16x16x32_bf16 v[118:121], v[144:147], v[184:187], v[118:121]
	v_mfma_f32_16x16x32_bf16 v[118:121], v[148:151], v[188:191], v[118:121]
	v_mfma_f32_16x16x32_bf16 v[102:105], v[144:147], v[192:195], v[102:105]
	v_mfma_f32_16x16x32_bf16 v[102:105], v[148:151], v[200:203], v[102:105]
	v_mfma_f32_16x16x32_bf16 v[86:89], v[144:147], v[204:207], v[86:89]
	v_mfma_f32_16x16x32_bf16 v[86:89], v[148:151], v[208:211], v[86:89]
	v_mfma_f32_16x16x32_bf16 v[122:125], v[152:155], v[176:179], v[122:125]
	v_mfma_f32_16x16x32_bf16 v[122:125], v[156:159], v[180:183], v[122:125]
	v_mfma_f32_16x16x32_bf16 v[114:117], v[152:155], v[184:187], v[114:117]
	v_mfma_f32_16x16x32_bf16 v[114:117], v[156:159], v[188:191], v[114:117]
	v_mfma_f32_16x16x32_bf16 v[98:101], v[152:155], v[192:195], v[98:101]
	v_mfma_f32_16x16x32_bf16 v[98:101], v[156:159], v[200:203], v[98:101]
	v_mfma_f32_16x16x32_bf16 v[82:85], v[152:155], v[204:207], v[82:85]
	v_mfma_f32_16x16x32_bf16 v[82:85], v[156:159], v[208:211], v[82:85]
	v_mfma_f32_16x16x32_bf16 v[110:113], v[160:163], v[176:179], v[110:113]
	v_mfma_f32_16x16x32_bf16 v[110:113], v[164:167], v[180:183], v[110:113]
	v_mfma_f32_16x16x32_bf16 v[94:97], v[160:163], v[184:187], v[94:97]
	v_mfma_f32_16x16x32_bf16 v[94:97], v[164:167], v[188:191], v[94:97]
	v_mfma_f32_16x16x32_bf16 v[78:81], v[160:163], v[192:195], v[78:81]
	v_mfma_f32_16x16x32_bf16 v[78:81], v[164:167], v[200:203], v[78:81]
	v_mfma_f32_16x16x32_bf16 v[70:73], v[160:163], v[204:207], v[70:73]
	v_mfma_f32_16x16x32_bf16 v[70:73], v[164:167], v[208:211], v[70:73]
	v_mfma_f32_16x16x32_bf16 v[106:109], v[168:171], v[176:179], v[106:109]
	v_mfma_f32_16x16x32_bf16 v[106:109], v[172:175], v[180:183], v[106:109]
	v_mfma_f32_16x16x32_bf16 v[90:93], v[168:171], v[184:187], v[90:93]
	v_mfma_f32_16x16x32_bf16 v[90:93], v[172:175], v[188:191], v[90:93]
	v_mfma_f32_16x16x32_bf16 v[74:77], v[168:171], v[192:195], v[74:77]
	v_mfma_f32_16x16x32_bf16 v[74:77], v[172:175], v[200:203], v[74:77]
	v_mfma_f32_16x16x32_bf16 v[66:69], v[168:171], v[204:207], v[66:69]
	v_mfma_f32_16x16x32_bf16 v[66:69], v[172:175], v[208:211], v[66:69]
	s_barrier
	s_add_u32 s98, s34, 0x80
	s_addc_u32 s99, s35, 0
	s_add_i32 s40, s54, s9
	s_mov_b32 m0, s40
	ds_read_b128 v[176:179], v143 offset:49152
	ds_read_b128 v[180:183], v143 offset:50176
	ds_read_b128 v[184:187], v143 offset:51200
	ds_read_b128 v[188:191], v143 offset:52224
	ds_read_b128 v[192:195], v143 offset:53248
	ds_read_b128 v[200:203], v143 offset:54272
	ds_read_b128 v[204:207], v143 offset:55296
	ds_read_b128 v[208:211], v143 offset:56320
	global_load_lds_dwordx4 v0, s[98:99]
	s_add_i32 m0, s40, 0x2000
	s_add_u32 s34, s34, 0x100080
	s_addc_u32 s35, s35, 0
	s_add_i32 s40, s55, s9
	global_load_lds_dwordx4 v130, s[98:99]
	s_mov_b32 m0, s40
	s_nop 0
	global_load_lds_dwordx4 v0, s[34:35]
	s_add_i32 m0, s40, 0x2000
	s_nop 0
	global_load_lds_dwordx4 v130, s[34:35]
	s_waitcnt vmcnt(6)
	s_waitcnt lgkmcnt(0)
	s_barrier
	s_waitcnt lgkmcnt(0)
	v_mfma_f32_16x16x32_bf16 v[62:65], v[144:147], v[176:179], v[62:65]
	v_mfma_f32_16x16x32_bf16 v[62:65], v[148:151], v[180:183], v[62:65]
	v_mfma_f32_16x16x32_bf16 v[54:57], v[144:147], v[184:187], v[54:57]
	v_mfma_f32_16x16x32_bf16 v[54:57], v[148:151], v[188:191], v[54:57]
	v_mfma_f32_16x16x32_bf16 v[38:41], v[144:147], v[192:195], v[38:41]
	v_mfma_f32_16x16x32_bf16 v[38:41], v[148:151], v[200:203], v[38:41]
	v_mfma_f32_16x16x32_bf16 v[22:25], v[144:147], v[204:207], v[22:25]
	v_mfma_f32_16x16x32_bf16 v[22:25], v[148:151], v[208:211], v[22:25]
	v_mfma_f32_16x16x32_bf16 v[58:61], v[152:155], v[176:179], v[58:61]
	v_mfma_f32_16x16x32_bf16 v[58:61], v[156:159], v[180:183], v[58:61]
	v_mfma_f32_16x16x32_bf16 v[50:53], v[152:155], v[184:187], v[50:53]
	v_mfma_f32_16x16x32_bf16 v[50:53], v[156:159], v[188:191], v[50:53]
	v_mfma_f32_16x16x32_bf16 v[34:37], v[152:155], v[192:195], v[34:37]
	v_mfma_f32_16x16x32_bf16 v[34:37], v[156:159], v[200:203], v[34:37]
	v_mfma_f32_16x16x32_bf16 v[18:21], v[152:155], v[204:207], v[18:21]
	v_mfma_f32_16x16x32_bf16 v[18:21], v[156:159], v[208:211], v[18:21]
	v_mfma_f32_16x16x32_bf16 v[46:49], v[160:163], v[176:179], v[46:49]
	v_mfma_f32_16x16x32_bf16 v[46:49], v[164:167], v[180:183], v[46:49]
	v_mfma_f32_16x16x32_bf16 v[30:33], v[160:163], v[184:187], v[30:33]
	v_mfma_f32_16x16x32_bf16 v[30:33], v[164:167], v[188:191], v[30:33]
	v_mfma_f32_16x16x32_bf16 v[14:17], v[160:163], v[192:195], v[14:17]
	v_mfma_f32_16x16x32_bf16 v[14:17], v[164:167], v[200:203], v[14:17]
	v_mfma_f32_16x16x32_bf16 v[6:9], v[160:163], v[204:207], v[6:9]
	v_mfma_f32_16x16x32_bf16 v[6:9], v[164:167], v[208:211], v[6:9]
	v_mfma_f32_16x16x32_bf16 v[42:45], v[168:171], v[176:179], v[42:45]
	v_mfma_f32_16x16x32_bf16 v[42:45], v[172:175], v[180:183], v[42:45]
	v_mfma_f32_16x16x32_bf16 v[26:29], v[168:171], v[184:187], v[26:29]
	v_mfma_f32_16x16x32_bf16 v[26:29], v[172:175], v[188:191], v[26:29]
	v_mfma_f32_16x16x32_bf16 v[10:13], v[168:171], v[192:195], v[10:13]
	v_mfma_f32_16x16x32_bf16 v[10:13], v[172:175], v[200:203], v[10:13]
	v_mfma_f32_16x16x32_bf16 v[2:5], v[168:171], v[204:207], v[2:5]
	v_mfma_f32_16x16x32_bf16 v[2:5], v[172:175], v[208:211], v[2:5]
	s_barrier
	s_add_i32 s53, s53, 2
	s_add_u32 s30, s30, 0x100
	s_addc_u32 s31, s31, 0
	s_add_u32 s51, s51, 0x100
	s_addc_u32 s52, s52, 0
	s_cmp_gt_u32 s53, 61
	s_cbranch_scc0 .LBB0_801
	s_and_b64 vcc, exec, s[20:21]
	s_cbranch_vccz .LBB0_804
	s_barrier
